# 1024 weight-transpose items (w_gate, w_up, most of w_down) now run on the idle phase-5 workgroups; scale-vector loads in the w_gate/w_up/w_mq transposes hoisted so the per-step vmcnt(0) (which drained
# speedup vs baseline: 1.1939x; 1.0116x over previous
.Lp5_idle:
	s_cmpk_eq_i32 s72, 0x200
	s_cbranch_scc0 .Lp5_idle_none
	s_add_u32 s46, s12, 8
	s_addc_u32 s47, s13, 0
	s_add_i32 s50, s60, 0x128
	s_movk_i32 s51, 0x100
	s_movk_i32 s52, 0x627
	s_mov_b32 s53, 0
	s_branch .Ltramp_p0b

.LBB0_362:
	s_andn2_b64 vcc, exec, s[40:41]
	s_cbranch_vccnz .Ltramp7a
	v_readlane_b32 s20, v209, 10
	v_readlane_b32 s21, v209, 11
	s_andn2_b64 vcc, exec, s[20:21]
	s_cbranch_vccnz .Ltramp7a
	s_add_u32 s46, s12, 8
	s_addc_u32 s47, s13, 0
	s_mov_b32 s50, s60
	s_mov_b32 s51, s72
	s_movk_i32 s52, 0xaf0
	s_mov_b32 s53, 0
	s_cmpk_eq_i32 s72, 0x200
	s_cbranch_scc0 .Lp0_head
	s_movk_i32 s52, 0x6f0
	s_movk_i32 s53, 0x400
	s_branch .Lp0_head

.LBB0_528:
	s_andn2_b64 vcc, exec, s[40:41]
	s_cbranch_vccnz .LBB0_546
	s_load_dwordx2 s[40:41], s[12:13], 0xe0
	s_load_dwordx2 s[22:23], s[12:13], 0xf0
	s_lshl_b32 s20, s8, 9
	s_and_b32 s21, s20, 0x600
	s_lshl_b32 s20, s8, 4
	s_add_i32 s20, s20, 0xfc780
	v_mov_b32_e32 v135, v131
	s_and_b32 s20, s20, 0xfffc0
	s_lshl_b32 s24, s20, 2
	v_ashrrev_i32_e32 v0, 2, v135
	v_and_b32_e32 v133, 15, v135
	v_and_b32_e32 v138, -4, v0
	s_waitcnt lgkmcnt(0)
	s_add_u32 s22, s22, s24
	v_add_u32_e32 v14, s21, v138
	s_addc_u32 s23, s23, 0
	v_lshlrev_b32_e32 v0, 4, v133
	v_lshl_add_u64 v[10:11], s[22:23], 0, v[0:1]
	s_movk_i32 s0, 0x5800
	v_or_b32_e32 v0, 1, v14
	v_mad_i64_i32 v[2:3], s[22:23], v14, s0, v[10:11]
	v_mad_i64_i32 v[4:5], s[22:23], v0, s0, v[10:11]
	v_or_b32_e32 v0, 2, v14
	global_load_dwordx4 v[114:117], v[2:3], off
	global_load_dwordx4 v[118:121], v[4:5], off
	v_mad_i64_i32 v[2:3], s[22:23], v0, s0, v[10:11]
	v_or_b32_e32 v0, 3, v14
	v_mad_i64_i32 v[4:5], s[22:23], v0, s0, v[10:11]
	v_add_u32_e32 v0, 64, v14
	global_load_dwordx4 v[122:125], v[2:3], off
	global_load_dwordx4 v[126:129], v[4:5], off
	v_mad_i64_i32 v[2:3], s[22:23], v0, s0, v[10:11]
	v_add_u32_e32 v0, 0x41, v14
	v_mad_i64_i32 v[4:5], s[22:23], v0, s0, v[10:11]
	v_add_u32_e32 v0, 0x42, v14
	global_load_dwordx4 v[98:101], v[2:3], off
	global_load_dwordx4 v[102:105], v[4:5], off
	v_mad_i64_i32 v[2:3], s[22:23], v0, s0, v[10:11]
	v_add_u32_e32 v0, 0x43, v14
	v_mad_i64_i32 v[4:5], s[22:23], v0, s0, v[10:11]
	v_add_u32_e32 v0, 0x80, v14
	global_load_dwordx4 v[106:109], v[2:3], off
	global_load_dwordx4 v[110:113], v[4:5], off
	v_mad_i64_i32 v[2:3], s[22:23], v0, s0, v[10:11]
	v_add_u32_e32 v0, 0x81, v14
	v_mad_i64_i32 v[4:5], s[22:23], v0, s0, v[10:11]
	v_add_u32_e32 v0, 0x82, v14
	global_load_dwordx4 v[82:85], v[2:3], off
	global_load_dwordx4 v[86:89], v[4:5], off
	v_mad_i64_i32 v[2:3], s[22:23], v0, s0, v[10:11]
	v_add_u32_e32 v0, 0x83, v14
	v_mad_i64_i32 v[4:5], s[22:23], v0, s0, v[10:11]
	v_add_u32_e32 v0, 0xc0, v14
	global_load_dwordx4 v[90:93], v[2:3], off
	global_load_dwordx4 v[94:97], v[4:5], off
	v_mad_i64_i32 v[2:3], s[22:23], v0, s0, v[10:11]
	v_add_u32_e32 v0, 0xc1, v14
	v_mad_i64_i32 v[4:5], s[22:23], v0, s0, v[10:11]
	v_add_u32_e32 v0, 0xc2, v14
	global_load_dwordx4 v[66:69], v[2:3], off
	global_load_dwordx4 v[70:73], v[4:5], off
	v_mad_i64_i32 v[2:3], s[22:23], v0, s0, v[10:11]
	v_add_u32_e32 v0, 0xc3, v14
	v_mad_i64_i32 v[4:5], s[22:23], v0, s0, v[10:11]
	v_add_u32_e32 v0, 0x100, v14
	global_load_dwordx4 v[74:77], v[2:3], off
	global_load_dwordx4 v[78:81], v[4:5], off
	v_mad_i64_i32 v[2:3], s[22:23], v0, s0, v[10:11]
	v_add_u32_e32 v0, 0x101, v14
	v_mad_i64_i32 v[4:5], s[22:23], v0, s0, v[10:11]
	v_add_u32_e32 v0, 0x102, v14
	global_load_dwordx4 v[50:53], v[2:3], off
	global_load_dwordx4 v[54:57], v[4:5], off
	v_mad_i64_i32 v[2:3], s[22:23], v0, s0, v[10:11]
	v_add_u32_e32 v0, 0x103, v14
	v_mad_i64_i32 v[4:5], s[22:23], v0, s0, v[10:11]
	v_add_u32_e32 v0, 0x140, v14
	global_load_dwordx4 v[58:61], v[2:3], off
	global_load_dwordx4 v[62:65], v[4:5], off
	v_mad_i64_i32 v[2:3], s[22:23], v0, s0, v[10:11]
	v_add_u32_e32 v0, 0x141, v14
	v_mad_i64_i32 v[4:5], s[22:23], v0, s0, v[10:11]
	v_add_u32_e32 v0, 0x142, v14
	global_load_dwordx4 v[34:37], v[2:3], off
	global_load_dwordx4 v[38:41], v[4:5], off
	v_mad_i64_i32 v[2:3], s[22:23], v0, s0, v[10:11]
	v_add_u32_e32 v0, 0x143, v14
	v_mad_i64_i32 v[4:5], s[22:23], v0, s0, v[10:11]
	v_add_u32_e32 v0, 0x180, v14
	global_load_dwordx4 v[42:45], v[2:3], off
	global_load_dwordx4 v[46:49], v[4:5], off
	v_mad_i64_i32 v[2:3], s[22:23], v0, s0, v[10:11]
	v_add_u32_e32 v0, 0x181, v14
	v_mad_i64_i32 v[4:5], s[22:23], v0, s0, v[10:11]
	v_add_u32_e32 v0, 0x182, v14
	global_load_dwordx4 v[18:21], v[2:3], off
	global_load_dwordx4 v[22:25], v[4:5], off
	v_mad_i64_i32 v[2:3], s[22:23], v0, s0, v[10:11]
	v_add_u32_e32 v0, 0x183, v14
	v_mad_i64_i32 v[4:5], s[22:23], v0, s0, v[10:11]
	v_add_u32_e32 v0, 0x1c0, v14
	global_load_dwordx4 v[26:29], v[2:3], off
	global_load_dwordx4 v[30:33], v[4:5], off
	v_mad_i64_i32 v[2:3], s[22:23], v0, s0, v[10:11]
	v_add_u32_e32 v0, 0x1c1, v14
	v_mad_i64_i32 v[6:7], s[22:23], v0, s0, v[10:11]
	v_add_u32_e32 v0, 0x1c2, v14
	v_mad_i64_i32 v[12:13], s[22:23], v0, s0, v[10:11]
	v_add_u32_e32 v0, 0x1c3, v14
	v_mad_i64_i32 v[14:15], s[22:23], v0, s0, v[10:11]
	global_load_dwordx4 v[2:5], v[2:3], off
	s_nop 0
	global_load_dwordx4 v[6:9], v[6:7], off
	s_nop 0
	global_load_dwordx4 v[10:13], v[12:13], off
	s_nop 0
	global_load_dwordx4 v[14:17], v[14:15], off
	s_cmp_lg_u64 s[40:41], 0
	s_cselect_b64 s[42:43], -1, 0
	s_lshl_b32 s22, s21, 2
	s_add_u32 s22, s40, s22
	s_addc_u32 s23, s41, 0
	v_ashrrev_i32_e32 v139, 31, v138
	s_cmp_eq_u64 s[40:41], 0
	v_lshl_add_u64 v[136:137], v[138:139], 2, s[22:23]
	s_cbranch_scc1 .LBB0_531
	global_load_dwordx4 v[140:143], v[136:137], off
	global_load_dwordx4 v[212:215], v[136:137], off offset:256
	global_load_dwordx4 v[216:219], v[136:137], off offset:512
	global_load_dwordx4 v[220:223], v[136:137], off offset:768
	global_load_dwordx4 v[224:227], v[136:137], off offset:1024
	global_load_dwordx4 v[228:231], v[136:137], off offset:1280
	global_load_dwordx4 v[232:235], v[136:137], off offset:1536
	global_load_dwordx4 v[236:239], v[136:137], off offset:1792
	s_waitcnt vmcnt(0)
	v_mov_b32_e32 v0, v143
	v_pk_mul_f32 v[114:115], v[114:115], v[140:141] op_sel_hi:[1,0]
	v_pk_mul_f32 v[116:117], v[116:117], v[140:141] op_sel_hi:[1,0]
	v_pk_mul_f32 v[118:119], v[118:119], v[140:141] op_sel:[0,1]
	v_pk_mul_f32 v[120:121], v[120:121], v[140:141] op_sel:[0,1]
	v_pk_mul_f32 v[122:123], v[122:123], v[142:143] op_sel_hi:[1,0]
	v_pk_mul_f32 v[124:125], v[124:125], v[142:143] op_sel_hi:[1,0]
	v_pk_mul_f32 v[126:127], v[126:127], v[0:1] op_sel_hi:[1,0]
	v_pk_mul_f32 v[128:129], v[128:129], v[0:1] op_sel_hi:[1,0]
.LBB0_531:
	s_load_dwordx2 s[22:23], s[12:13], 0x130
	v_mul_u32_u24_e32 v0, 0x240, v133
	v_lshlrev_b32_e32 v133, 1, v138
	s_lshl_b32 s21, s21, 1
	v_add3_u32 v133, 16, v0, v133
	v_lshlrev_b32_e32 v0, 4, v135
	s_waitcnt lgkmcnt(0)
	s_add_u32 s22, s22, s21
	v_ashrrev_i32_e32 v142, 3, v135
	v_and_b32_e32 v0, 0x70, v0
	s_addc_u32 s23, s23, 0
	v_add_u32_e32 v135, 16, v0
	v_lshl_add_u64 v[138:139], s[22:23], 0, v[0:1]
	v_mul_lo_u32 v0, v142, s9
	s_waitcnt vmcnt(28)
	v_cvt_pk_bf16_f32 v141, v122, v126
	v_cvt_pk_bf16_f32 v140, v114, v118
	v_cvt_pk_bf16_f32 v123, v123, v127
	v_cvt_pk_bf16_f32 v122, v115, v119
	v_cvt_pk_bf16_f32 v115, v124, v128
	v_cvt_pk_bf16_f32 v114, v116, v120
	v_cvt_pk_bf16_f32 v119, v125, v129
	v_cvt_pk_bf16_f32 v118, v117, v121
	v_add_u32_e32 v0, v135, v0
	s_barrier
	ds_write2_b64 v133, v[140:141], v[122:123] offset1:18
	ds_write2_b64 v133, v[114:115], v[118:119] offset0:36 offset1:54
	s_waitcnt lgkmcnt(0)
	s_barrier
	ds_read_b128 v[116:119], v0
	v_add_lshl_u32 v124, v142, s20, 1
	v_and_b32_e32 v143, 31, v142
	v_and_b32_e32 v114, 0xffffffc0, v124
	v_or3_b32 v114, v143, v114, 32
	v_mad_i64_i32 v[114:115], s[20:21], v114, s81, v[138:139]
	ds_read_b128 v[120:123], v0 offset:4608
	s_waitcnt lgkmcnt(1)
	global_store_dwordx4 v[114:115], v[116:119], off
	s_andn2_b64 vcc, exec, s[42:43]
	s_nop 0
	v_add_u32_e32 v116, 64, v124
	v_and_b32_e32 v116, 0xffffffc0, v116
	v_or3_b32 v116, v143, v116, 32
	v_cndmask_b32_e64 v118, 0, 1, s[42:43]
	v_mad_i64_i32 v[116:117], s[20:21], v116, s81, v[138:139]
	v_cmp_ne_u32_e64 s[40:41], 1, v118
	s_waitcnt lgkmcnt(0)
	global_store_dwordx4 v[116:117], v[120:123], off
	s_cbranch_vccnz .LBB0_533
	v_pk_mul_f32 v[98:99], v[98:99], v[212:213] op_sel_hi:[1,0]
	v_pk_mul_f32 v[100:101], v[100:101], v[212:213] op_sel_hi:[1,0]
	v_pk_mul_f32 v[102:103], v[102:103], v[212:213] op_sel:[0,1]
	v_pk_mul_f32 v[104:105], v[104:105], v[212:213] op_sel:[0,1]
	v_mov_b32_e32 v212, v215
	v_pk_mul_f32 v[106:107], v[106:107], v[214:215] op_sel_hi:[1,0]
	v_pk_mul_f32 v[108:109], v[108:109], v[214:215] op_sel_hi:[1,0]
	v_pk_mul_f32 v[110:111], v[110:111], v[212:213] op_sel_hi:[1,0]
	v_pk_mul_f32 v[112:113], v[112:113], v[212:213] op_sel_hi:[1,0]
.LBB0_533:
	s_waitcnt vmcnt(26)
	v_cvt_pk_bf16_f32 v119, v106, v110
	v_cvt_pk_bf16_f32 v118, v98, v102
	v_cvt_pk_bf16_f32 v107, v107, v111
	v_cvt_pk_bf16_f32 v106, v99, v103
	v_cvt_pk_bf16_f32 v99, v108, v112
	v_cvt_pk_bf16_f32 v98, v100, v104
	v_cvt_pk_bf16_f32 v103, v109, v113
	v_cvt_pk_bf16_f32 v102, v101, v105
	s_barrier
	ds_write2_b64 v133, v[118:119], v[106:107] offset1:18
	ds_write2_b64 v133, v[98:99], v[102:103] offset0:36 offset1:54
	s_waitcnt lgkmcnt(0)
	s_barrier
	ds_read_b128 v[98:101], v0
	ds_read_b128 v[102:105], v0 offset:4608
	s_and_b64 vcc, exec, s[40:41]
	s_waitcnt lgkmcnt(1)
	global_store_dwordx4 v[114:115], v[98:101], off offset:128
	s_waitcnt lgkmcnt(0)
	global_store_dwordx4 v[116:117], v[102:105], off offset:128
	s_cbranch_vccnz .LBB0_535
	v_pk_mul_f32 v[82:83], v[82:83], v[216:217] op_sel_hi:[1,0]
	v_pk_mul_f32 v[84:85], v[84:85], v[216:217] op_sel_hi:[1,0]
	v_pk_mul_f32 v[86:87], v[86:87], v[216:217] op_sel:[0,1]
	v_pk_mul_f32 v[88:89], v[88:89], v[216:217] op_sel:[0,1]
	v_mov_b32_e32 v216, v219
	v_pk_mul_f32 v[90:91], v[90:91], v[218:219] op_sel_hi:[1,0]
	v_pk_mul_f32 v[92:93], v[92:93], v[218:219] op_sel_hi:[1,0]
	v_pk_mul_f32 v[94:95], v[94:95], v[216:217] op_sel_hi:[1,0]
	v_pk_mul_f32 v[96:97], v[96:97], v[216:217] op_sel_hi:[1,0]
.LBB0_535:
	s_waitcnt vmcnt(24)
	v_cvt_pk_bf16_f32 v99, v90, v94
	v_cvt_pk_bf16_f32 v98, v82, v86
	v_cvt_pk_bf16_f32 v91, v91, v95
	v_cvt_pk_bf16_f32 v90, v83, v87
	v_cvt_pk_bf16_f32 v83, v92, v96
	v_cvt_pk_bf16_f32 v82, v84, v88
	v_cvt_pk_bf16_f32 v87, v93, v97
	v_cvt_pk_bf16_f32 v86, v85, v89
	s_barrier
	ds_write2_b64 v133, v[98:99], v[90:91] offset1:18
	ds_write2_b64 v133, v[82:83], v[86:87] offset0:36 offset1:54
	s_waitcnt lgkmcnt(0)
	s_barrier
	ds_read_b128 v[82:85], v0
	ds_read_b128 v[86:89], v0 offset:4608
	s_and_b64 vcc, exec, s[40:41]
	s_waitcnt lgkmcnt(1)
	global_store_dwordx4 v[114:115], v[82:85], off offset:256
	s_waitcnt lgkmcnt(0)
	global_store_dwordx4 v[116:117], v[86:89], off offset:256
	s_cbranch_vccnz .LBB0_537
	v_pk_mul_f32 v[66:67], v[66:67], v[220:221] op_sel_hi:[1,0]
	v_pk_mul_f32 v[68:69], v[68:69], v[220:221] op_sel_hi:[1,0]
	v_pk_mul_f32 v[70:71], v[70:71], v[220:221] op_sel:[0,1]
	v_pk_mul_f32 v[72:73], v[72:73], v[220:221] op_sel:[0,1]
	v_mov_b32_e32 v220, v223
	v_pk_mul_f32 v[74:75], v[74:75], v[222:223] op_sel_hi:[1,0]
	v_pk_mul_f32 v[76:77], v[76:77], v[222:223] op_sel_hi:[1,0]
	v_pk_mul_f32 v[78:79], v[78:79], v[220:221] op_sel_hi:[1,0]
	v_pk_mul_f32 v[80:81], v[80:81], v[220:221] op_sel_hi:[1,0]
.LBB0_537:
	s_waitcnt vmcnt(22)
	v_cvt_pk_bf16_f32 v83, v74, v78
	v_cvt_pk_bf16_f32 v82, v66, v70
	v_cvt_pk_bf16_f32 v75, v75, v79
	v_cvt_pk_bf16_f32 v74, v67, v71
	v_cvt_pk_bf16_f32 v67, v76, v80
	v_cvt_pk_bf16_f32 v66, v68, v72
	v_cvt_pk_bf16_f32 v71, v77, v81
	v_cvt_pk_bf16_f32 v70, v69, v73
	s_barrier
	ds_write2_b64 v133, v[82:83], v[74:75] offset1:18
	ds_write2_b64 v133, v[66:67], v[70:71] offset0:36 offset1:54
	s_waitcnt lgkmcnt(0)
	s_barrier
	ds_read_b128 v[66:69], v0
	ds_read_b128 v[70:73], v0 offset:4608
	s_and_b64 vcc, exec, s[40:41]
	s_waitcnt lgkmcnt(1)
	global_store_dwordx4 v[114:115], v[66:69], off offset:384
	s_waitcnt lgkmcnt(0)
	global_store_dwordx4 v[116:117], v[70:73], off offset:384
	s_cbranch_vccnz .LBB0_539
	v_pk_mul_f32 v[50:51], v[50:51], v[224:225] op_sel_hi:[1,0]
	v_pk_mul_f32 v[52:53], v[52:53], v[224:225] op_sel_hi:[1,0]
	v_pk_mul_f32 v[54:55], v[54:55], v[224:225] op_sel:[0,1]
	v_pk_mul_f32 v[56:57], v[56:57], v[224:225] op_sel:[0,1]
	v_mov_b32_e32 v224, v227
	v_pk_mul_f32 v[58:59], v[58:59], v[226:227] op_sel_hi:[1,0]
	v_pk_mul_f32 v[60:61], v[60:61], v[226:227] op_sel_hi:[1,0]
	v_pk_mul_f32 v[62:63], v[62:63], v[224:225] op_sel_hi:[1,0]
	v_pk_mul_f32 v[64:65], v[64:65], v[224:225] op_sel_hi:[1,0]
.LBB0_539:
	s_waitcnt vmcnt(20)
	v_cvt_pk_bf16_f32 v67, v58, v62
	v_cvt_pk_bf16_f32 v66, v50, v54
	v_cvt_pk_bf16_f32 v59, v59, v63
	v_cvt_pk_bf16_f32 v58, v51, v55
	v_cvt_pk_bf16_f32 v51, v60, v64
	v_cvt_pk_bf16_f32 v50, v52, v56
	v_cvt_pk_bf16_f32 v55, v61, v65
	v_cvt_pk_bf16_f32 v54, v53, v57
	s_barrier
	ds_write2_b64 v133, v[66:67], v[58:59] offset1:18
	ds_write2_b64 v133, v[50:51], v[54:55] offset0:36 offset1:54
	s_waitcnt lgkmcnt(0)
	s_barrier
	ds_read_b128 v[50:53], v0
	ds_read_b128 v[54:57], v0 offset:4608
	s_and_b64 vcc, exec, s[40:41]
	s_waitcnt lgkmcnt(1)
	global_store_dwordx4 v[114:115], v[50:53], off offset:512
	s_waitcnt lgkmcnt(0)
	global_store_dwordx4 v[116:117], v[54:57], off offset:512
	s_cbranch_vccnz .LBB0_541
	v_pk_mul_f32 v[34:35], v[34:35], v[228:229] op_sel_hi:[1,0]
	v_pk_mul_f32 v[36:37], v[36:37], v[228:229] op_sel_hi:[1,0]
	v_pk_mul_f32 v[38:39], v[38:39], v[228:229] op_sel:[0,1]
	v_pk_mul_f32 v[40:41], v[40:41], v[228:229] op_sel:[0,1]
	v_mov_b32_e32 v228, v231
	v_pk_mul_f32 v[42:43], v[42:43], v[230:231] op_sel_hi:[1,0]
	v_pk_mul_f32 v[44:45], v[44:45], v[230:231] op_sel_hi:[1,0]
	v_pk_mul_f32 v[46:47], v[46:47], v[228:229] op_sel_hi:[1,0]
	v_pk_mul_f32 v[48:49], v[48:49], v[228:229] op_sel_hi:[1,0]
.LBB0_541:
	s_waitcnt vmcnt(18)
	v_cvt_pk_bf16_f32 v51, v42, v46
	v_cvt_pk_bf16_f32 v50, v34, v38
	v_cvt_pk_bf16_f32 v43, v43, v47
	v_cvt_pk_bf16_f32 v42, v35, v39
	v_cvt_pk_bf16_f32 v35, v44, v48
	v_cvt_pk_bf16_f32 v34, v36, v40
	v_cvt_pk_bf16_f32 v39, v45, v49
	v_cvt_pk_bf16_f32 v38, v37, v41
	s_barrier
	ds_write2_b64 v133, v[50:51], v[42:43] offset1:18
	ds_write2_b64 v133, v[34:35], v[38:39] offset0:36 offset1:54
	s_waitcnt lgkmcnt(0)
	s_barrier
	ds_read_b128 v[34:37], v0
	ds_read_b128 v[38:41], v0 offset:4608
	s_and_b64 vcc, exec, s[40:41]
	s_waitcnt lgkmcnt(1)
	global_store_dwordx4 v[114:115], v[34:37], off offset:640
	s_waitcnt lgkmcnt(0)
	global_store_dwordx4 v[116:117], v[38:41], off offset:640
	s_cbranch_vccnz .LBB0_543
	v_pk_mul_f32 v[18:19], v[18:19], v[232:233] op_sel_hi:[1,0]
	v_pk_mul_f32 v[20:21], v[20:21], v[232:233] op_sel_hi:[1,0]
	v_pk_mul_f32 v[22:23], v[22:23], v[232:233] op_sel:[0,1]
	v_pk_mul_f32 v[24:25], v[24:25], v[232:233] op_sel:[0,1]
	v_mov_b32_e32 v232, v235
	v_pk_mul_f32 v[26:27], v[26:27], v[234:235] op_sel_hi:[1,0]
	v_pk_mul_f32 v[28:29], v[28:29], v[234:235] op_sel_hi:[1,0]
	v_pk_mul_f32 v[30:31], v[30:31], v[232:233] op_sel_hi:[1,0]
	v_pk_mul_f32 v[32:33], v[32:33], v[232:233] op_sel_hi:[1,0]
.LBB0_543:
	s_waitcnt vmcnt(16)
	v_cvt_pk_bf16_f32 v35, v26, v30
	v_cvt_pk_bf16_f32 v34, v18, v22
	v_cvt_pk_bf16_f32 v27, v27, v31
	v_cvt_pk_bf16_f32 v26, v19, v23
	v_cvt_pk_bf16_f32 v19, v28, v32
	v_cvt_pk_bf16_f32 v18, v20, v24
	v_cvt_pk_bf16_f32 v23, v29, v33
	v_cvt_pk_bf16_f32 v22, v21, v25
	s_barrier
	ds_write2_b64 v133, v[34:35], v[26:27] offset1:18
	ds_write2_b64 v133, v[18:19], v[22:23] offset0:36 offset1:54
	s_waitcnt lgkmcnt(0)
	s_barrier
	ds_read_b128 v[18:21], v0
	ds_read_b128 v[22:25], v0 offset:4608
	s_and_b64 vcc, exec, s[40:41]
	s_waitcnt lgkmcnt(1)
	global_store_dwordx4 v[114:115], v[18:21], off offset:768
	s_waitcnt lgkmcnt(0)
	global_store_dwordx4 v[116:117], v[22:25], off offset:768
	s_cbranch_vccnz .LBB0_545
	v_pk_mul_f32 v[2:3], v[2:3], v[236:237] op_sel_hi:[1,0]
	v_pk_mul_f32 v[4:5], v[4:5], v[236:237] op_sel_hi:[1,0]
	v_pk_mul_f32 v[6:7], v[6:7], v[236:237] op_sel:[0,1]
	v_pk_mul_f32 v[8:9], v[8:9], v[236:237] op_sel:[0,1]
	v_mov_b32_e32 v236, v239
	v_pk_mul_f32 v[10:11], v[10:11], v[238:239] op_sel_hi:[1,0]
	v_pk_mul_f32 v[12:13], v[12:13], v[238:239] op_sel_hi:[1,0]
	v_pk_mul_f32 v[14:15], v[14:15], v[236:237] op_sel_hi:[1,0]
	v_pk_mul_f32 v[16:17], v[16:17], v[236:237] op_sel_hi:[1,0]

.LBB0_547:
	s_andn2_b64 vcc, exec, s[40:41]
	s_cbranch_vccnz .LBB0_565
	s_load_dwordx4 s[40:43], s[12:13], 0xe0
	s_lshl_b32 s20, s8, 9
	s_and_b32 s21, s20, 0x600
	s_lshl_b32 s20, s8, 4
	s_add_i32 s20, s20, 0xfdd80
	v_mov_b32_e32 v135, v131
	s_and_b32 s20, s20, 0xfffc0
	s_lshl_b32 s22, s20, 2
	v_ashrrev_i32_e32 v0, 2, v135
	v_and_b32_e32 v133, 15, v135
	v_and_b32_e32 v138, -4, v0
	s_waitcnt lgkmcnt(0)
	s_add_u32 s22, s42, s22
	v_add_u32_e32 v14, s21, v138
	s_addc_u32 s23, s43, 0
	v_lshlrev_b32_e32 v0, 4, v133
	v_lshl_add_u64 v[10:11], s[22:23], 0, v[0:1]
	s_movk_i32 s0, 0x5800
	v_or_b32_e32 v0, 1, v14
	v_mad_i64_i32 v[2:3], s[22:23], v14, s0, v[10:11]
	v_mad_i64_i32 v[4:5], s[22:23], v0, s0, v[10:11]
	v_or_b32_e32 v0, 2, v14
	global_load_dwordx4 v[114:117], v[2:3], off
	global_load_dwordx4 v[118:121], v[4:5], off
	v_mad_i64_i32 v[2:3], s[22:23], v0, s0, v[10:11]
	v_or_b32_e32 v0, 3, v14
	v_mad_i64_i32 v[4:5], s[22:23], v0, s0, v[10:11]
	v_add_u32_e32 v0, 64, v14
	global_load_dwordx4 v[122:125], v[2:3], off
	global_load_dwordx4 v[126:129], v[4:5], off
	v_mad_i64_i32 v[2:3], s[22:23], v0, s0, v[10:11]
	v_add_u32_e32 v0, 0x41, v14
	v_mad_i64_i32 v[4:5], s[22:23], v0, s0, v[10:11]
	v_add_u32_e32 v0, 0x42, v14
	global_load_dwordx4 v[98:101], v[2:3], off
	global_load_dwordx4 v[102:105], v[4:5], off
	v_mad_i64_i32 v[2:3], s[22:23], v0, s0, v[10:11]
	v_add_u32_e32 v0, 0x43, v14
	v_mad_i64_i32 v[4:5], s[22:23], v0, s0, v[10:11]
	v_add_u32_e32 v0, 0x80, v14
	global_load_dwordx4 v[106:109], v[2:3], off
	global_load_dwordx4 v[110:113], v[4:5], off
	v_mad_i64_i32 v[2:3], s[22:23], v0, s0, v[10:11]
	v_add_u32_e32 v0, 0x81, v14
	v_mad_i64_i32 v[4:5], s[22:23], v0, s0, v[10:11]
	v_add_u32_e32 v0, 0x82, v14
	global_load_dwordx4 v[82:85], v[2:3], off
	global_load_dwordx4 v[86:89], v[4:5], off
	v_mad_i64_i32 v[2:3], s[22:23], v0, s0, v[10:11]
	v_add_u32_e32 v0, 0x83, v14
	v_mad_i64_i32 v[4:5], s[22:23], v0, s0, v[10:11]
	v_add_u32_e32 v0, 0xc0, v14
	global_load_dwordx4 v[90:93], v[2:3], off
	global_load_dwordx4 v[94:97], v[4:5], off
	v_mad_i64_i32 v[2:3], s[22:23], v0, s0, v[10:11]
	v_add_u32_e32 v0, 0xc1, v14
	v_mad_i64_i32 v[4:5], s[22:23], v0, s0, v[10:11]
	v_add_u32_e32 v0, 0xc2, v14
	global_load_dwordx4 v[66:69], v[2:3], off
	global_load_dwordx4 v[70:73], v[4:5], off
	v_mad_i64_i32 v[2:3], s[22:23], v0, s0, v[10:11]
	v_add_u32_e32 v0, 0xc3, v14
	v_mad_i64_i32 v[4:5], s[22:23], v0, s0, v[10:11]
	v_add_u32_e32 v0, 0x100, v14
	global_load_dwordx4 v[74:77], v[2:3], off
	global_load_dwordx4 v[78:81], v[4:5], off
	v_mad_i64_i32 v[2:3], s[22:23], v0, s0, v[10:11]
	v_add_u32_e32 v0, 0x101, v14
	v_mad_i64_i32 v[4:5], s[22:23], v0, s0, v[10:11]
	v_add_u32_e32 v0, 0x102, v14
	global_load_dwordx4 v[50:53], v[2:3], off
	global_load_dwordx4 v[54:57], v[4:5], off
	v_mad_i64_i32 v[2:3], s[22:23], v0, s0, v[10:11]
	v_add_u32_e32 v0, 0x103, v14
	v_mad_i64_i32 v[4:5], s[22:23], v0, s0, v[10:11]
	v_add_u32_e32 v0, 0x140, v14
	global_load_dwordx4 v[58:61], v[2:3], off
	global_load_dwordx4 v[62:65], v[4:5], off
	v_mad_i64_i32 v[2:3], s[22:23], v0, s0, v[10:11]
	v_add_u32_e32 v0, 0x141, v14
	v_mad_i64_i32 v[4:5], s[22:23], v0, s0, v[10:11]
	v_add_u32_e32 v0, 0x142, v14
	global_load_dwordx4 v[34:37], v[2:3], off
	global_load_dwordx4 v[38:41], v[4:5], off
	v_mad_i64_i32 v[2:3], s[22:23], v0, s0, v[10:11]
	v_add_u32_e32 v0, 0x143, v14
	v_mad_i64_i32 v[4:5], s[22:23], v0, s0, v[10:11]
	v_add_u32_e32 v0, 0x180, v14
	global_load_dwordx4 v[42:45], v[2:3], off
	global_load_dwordx4 v[46:49], v[4:5], off
	v_mad_i64_i32 v[2:3], s[22:23], v0, s0, v[10:11]
	v_add_u32_e32 v0, 0x181, v14
	v_mad_i64_i32 v[4:5], s[22:23], v0, s0, v[10:11]
	v_add_u32_e32 v0, 0x182, v14
	global_load_dwordx4 v[18:21], v[2:3], off
	global_load_dwordx4 v[22:25], v[4:5], off
	v_mad_i64_i32 v[2:3], s[22:23], v0, s0, v[10:11]
	v_add_u32_e32 v0, 0x183, v14
	v_mad_i64_i32 v[4:5], s[22:23], v0, s0, v[10:11]
	v_add_u32_e32 v0, 0x1c0, v14
	global_load_dwordx4 v[26:29], v[2:3], off
	global_load_dwordx4 v[30:33], v[4:5], off
	v_mad_i64_i32 v[2:3], s[22:23], v0, s0, v[10:11]
	v_add_u32_e32 v0, 0x1c1, v14
	v_mad_i64_i32 v[6:7], s[22:23], v0, s0, v[10:11]
	v_add_u32_e32 v0, 0x1c2, v14
	v_mad_i64_i32 v[12:13], s[22:23], v0, s0, v[10:11]
	v_add_u32_e32 v0, 0x1c3, v14
	v_mad_i64_i32 v[14:15], s[22:23], v0, s0, v[10:11]
	global_load_dwordx4 v[2:5], v[2:3], off
	s_nop 0
	global_load_dwordx4 v[6:9], v[6:7], off
	s_nop 0
	global_load_dwordx4 v[10:13], v[12:13], off
	s_nop 0
	global_load_dwordx4 v[14:17], v[14:15], off
	s_cmp_lg_u64 s[40:41], 0
	s_cselect_b64 s[42:43], -1, 0
	s_lshl_b32 s22, s21, 2
	s_add_u32 s22, s40, s22
	s_addc_u32 s23, s41, 0
	v_ashrrev_i32_e32 v139, 31, v138
	s_cmp_eq_u64 s[40:41], 0
	v_lshl_add_u64 v[136:137], v[138:139], 2, s[22:23]
	s_cbranch_scc1 .LBB0_550
	global_load_dwordx4 v[140:143], v[136:137], off
	global_load_dwordx4 v[212:215], v[136:137], off offset:256
	global_load_dwordx4 v[216:219], v[136:137], off offset:512
	global_load_dwordx4 v[220:223], v[136:137], off offset:768
	global_load_dwordx4 v[224:227], v[136:137], off offset:1024
	global_load_dwordx4 v[228:231], v[136:137], off offset:1280
	global_load_dwordx4 v[232:235], v[136:137], off offset:1536
	global_load_dwordx4 v[236:239], v[136:137], off offset:1792
	s_waitcnt vmcnt(0)
	v_mov_b32_e32 v0, v143
	v_pk_mul_f32 v[114:115], v[114:115], v[140:141] op_sel_hi:[1,0]
	v_pk_mul_f32 v[116:117], v[116:117], v[140:141] op_sel_hi:[1,0]
	v_pk_mul_f32 v[118:119], v[118:119], v[140:141] op_sel:[0,1]
	v_pk_mul_f32 v[120:121], v[120:121], v[140:141] op_sel:[0,1]
	v_pk_mul_f32 v[122:123], v[122:123], v[142:143] op_sel_hi:[1,0]
	v_pk_mul_f32 v[124:125], v[124:125], v[142:143] op_sel_hi:[1,0]
	v_pk_mul_f32 v[126:127], v[126:127], v[0:1] op_sel_hi:[1,0]
	v_pk_mul_f32 v[128:129], v[128:129], v[0:1] op_sel_hi:[1,0]
.LBB0_550:
	s_load_dwordx2 s[22:23], s[12:13], 0x130
	v_mul_u32_u24_e32 v0, 0x240, v133
	v_lshlrev_b32_e32 v133, 1, v138
	s_lshl_b32 s21, s21, 1
	v_add3_u32 v133, 16, v0, v133
	v_lshlrev_b32_e32 v0, 4, v135
	s_waitcnt lgkmcnt(0)
	s_add_u32 s22, s22, s21
	v_ashrrev_i32_e32 v142, 3, v135
	v_and_b32_e32 v0, 0x70, v0
	s_addc_u32 s23, s23, 0
	v_add_u32_e32 v135, 16, v0
	v_lshl_add_u64 v[138:139], s[22:23], 0, v[0:1]
	v_mul_lo_u32 v0, v142, s9
	s_waitcnt vmcnt(28)
	v_cvt_pk_bf16_f32 v141, v122, v126
	v_cvt_pk_bf16_f32 v140, v114, v118
	v_cvt_pk_bf16_f32 v123, v123, v127
	v_cvt_pk_bf16_f32 v122, v115, v119
	v_cvt_pk_bf16_f32 v115, v124, v128
	v_cvt_pk_bf16_f32 v114, v116, v120
	v_cvt_pk_bf16_f32 v119, v125, v129
	v_cvt_pk_bf16_f32 v118, v117, v121
	v_add_u32_e32 v0, v135, v0
	s_barrier
	ds_write2_b64 v133, v[140:141], v[122:123] offset1:18
	ds_write2_b64 v133, v[114:115], v[118:119] offset0:36 offset1:54
	s_waitcnt lgkmcnt(0)
	s_barrier
	ds_read_b128 v[116:119], v0
	v_and_b32_e32 v143, 31, v142
	v_add_lshl_u32 v124, v142, s20, 1
	s_movk_i32 s22, 0xffc0
	v_and_or_b32 v114, v124, s22, v143
	ds_read_b128 v[120:123], v0 offset:4608
	v_mad_i64_i32 v[114:115], s[20:21], v114, s81, v[138:139]
	s_waitcnt lgkmcnt(1)
	global_store_dwordx4 v[114:115], v[116:119], off
	s_andn2_b64 vcc, exec, s[42:43]
	s_nop 0
	v_add_u32_e32 v116, 64, v124
	v_and_or_b32 v116, v116, s22, v143
	v_cndmask_b32_e64 v118, 0, 1, s[42:43]
	v_mad_i64_i32 v[116:117], s[20:21], v116, s81, v[138:139]
	v_cmp_ne_u32_e64 s[40:41], 1, v118
	s_waitcnt lgkmcnt(0)
	global_store_dwordx4 v[116:117], v[120:123], off
	s_cbranch_vccnz .LBB0_552
	v_pk_mul_f32 v[98:99], v[98:99], v[212:213] op_sel_hi:[1,0]
	v_pk_mul_f32 v[100:101], v[100:101], v[212:213] op_sel_hi:[1,0]
	v_pk_mul_f32 v[102:103], v[102:103], v[212:213] op_sel:[0,1]
	v_pk_mul_f32 v[104:105], v[104:105], v[212:213] op_sel:[0,1]
	v_mov_b32_e32 v212, v215
	v_pk_mul_f32 v[106:107], v[106:107], v[214:215] op_sel_hi:[1,0]
	v_pk_mul_f32 v[108:109], v[108:109], v[214:215] op_sel_hi:[1,0]
	v_pk_mul_f32 v[110:111], v[110:111], v[212:213] op_sel_hi:[1,0]
	v_pk_mul_f32 v[112:113], v[112:113], v[212:213] op_sel_hi:[1,0]

.LBB0_569:
	s_andn2_b64 vcc, exec, s[40:41]
	s_cbranch_vccnz .LBB0_587
	s_load_dwordx2 s[40:41], s[12:13], 0xa0
	s_load_dwordx2 s[22:23], s[12:13], 0xb0
	s_lshl_b32 s20, s8, 9
	v_mov_b32_e32 v135, v131
	s_and_b32 s21, s20, 0x600
	s_lshl_b32 s20, s8, 4
	s_addk_i32 s20, 0x180
	v_ashrrev_i32_e32 v0, 2, v135
	s_and_b32 s20, s20, 0xfc0
	v_and_b32_e32 v138, -4, v0
	s_waitcnt lgkmcnt(0)
	v_add_u32_e32 v2, s21, v138
	s_lshl_b32 s24, s20, 2
	v_and_b32_e32 v133, 15, v135
	s_add_u32 s22, s22, s24
	v_or_b32_e32 v8, 1, v2
	s_addc_u32 s23, s23, 0
	v_lshlrev_b32_e32 v0, 4, v133
	v_ashrrev_i32_e32 v3, 31, v2
	v_ashrrev_i32_e32 v9, 31, v8
	v_lshl_add_u64 v[4:5], s[22:23], 0, v[0:1]
	v_lshlrev_b64 v[6:7], 11, v[2:3]
	v_lshlrev_b64 v[8:9], 11, v[8:9]
	v_lshl_add_u64 v[6:7], v[4:5], 0, v[6:7]
	v_lshl_add_u64 v[8:9], v[4:5], 0, v[8:9]
	global_load_dwordx4 v[110:113], v[6:7], off
	global_load_dwordx4 v[114:117], v[8:9], off
	v_or_b32_e32 v8, 2, v2
	v_or_b32_e32 v2, 3, v2
	v_ashrrev_i32_e32 v9, 31, v8
	v_ashrrev_i32_e32 v3, 31, v2
	v_lshlrev_b64 v[8:9], 11, v[8:9]
	v_lshlrev_b64 v[2:3], 11, v[2:3]
	v_lshl_add_u64 v[8:9], v[4:5], 0, v[8:9]
	v_lshl_add_u64 v[2:3], v[4:5], 0, v[2:3]
	s_mov_b32 s0, 0x20000
	global_load_dwordx4 v[118:121], v[8:9], off
	global_load_dwordx4 v[122:125], v[2:3], off
	v_add_co_u32_e32 v2, vcc, s0, v6
	s_mov_b32 s0, 0x21000
	s_nop 0
	v_addc_co_u32_e32 v3, vcc, 0, v7, vcc
	v_add_co_u32_e32 v8, vcc, s0, v6
	s_mov_b32 s0, 0x40000
	s_nop 0
	v_addc_co_u32_e32 v9, vcc, 0, v7, vcc
	v_add_co_u32_e32 v4, vcc, s0, v6
	s_mov_b32 s0, 0x41000
	s_nop 0
	v_addc_co_u32_e32 v5, vcc, 0, v7, vcc
	v_add_co_u32_e32 v10, vcc, s0, v6
	s_mov_b32 s0, 0x60000
	s_nop 0
	v_addc_co_u32_e32 v11, vcc, 0, v7, vcc
	global_load_dwordx4 v[98:101], v[8:9], off
	global_load_dwordx4 v[102:105], v[8:9], off offset:2048
	global_load_dwordx4 v[106:109], v[2:3], off offset:2048
	global_load_dwordx4 v[82:85], v[4:5], off offset:2048
	global_load_dwordx4 v[86:89], v[10:11], off offset:-4096
	global_load_dwordx4 v[90:93], v[10:11], off
	v_add_co_u32_e32 v2, vcc, s0, v6
	s_mov_b32 s0, 0x61000
	s_nop 0
	v_addc_co_u32_e32 v3, vcc, 0, v7, vcc
	v_add_co_u32_e32 v4, vcc, s0, v6
	s_mov_b32 s0, 0x80000
	s_nop 0
	v_addc_co_u32_e32 v5, vcc, 0, v7, vcc
	global_load_dwordx4 v[94:97], v[10:11], off offset:2048
	global_load_dwordx4 v[66:69], v[4:5], off offset:-4096
	global_load_dwordx4 v[70:73], v[4:5], off
	global_load_dwordx4 v[74:77], v[4:5], off offset:2048
	v_add_co_u32_e32 v4, vcc, s0, v6
	s_mov_b32 s0, 0x81000
	s_nop 0
	v_addc_co_u32_e32 v5, vcc, 0, v7, vcc
	v_add_co_u32_e32 v10, vcc, s0, v6
	s_mov_b32 s0, 0xa0000
	s_nop 0
	v_addc_co_u32_e32 v11, vcc, 0, v7, vcc
	global_load_dwordx4 v[78:81], v[2:3], off offset:2048
	global_load_dwordx4 v[50:53], v[4:5], off offset:2048
	global_load_dwordx4 v[54:57], v[10:11], off offset:-4096
	global_load_dwordx4 v[58:61], v[10:11], off
	v_add_co_u32_e32 v2, vcc, s0, v6
	s_mov_b32 s0, 0xa1000
	s_nop 0
	v_addc_co_u32_e32 v3, vcc, 0, v7, vcc
	v_add_co_u32_e32 v4, vcc, s0, v6
	s_mov_b32 s0, 0xc0000
	s_nop 0
	v_addc_co_u32_e32 v5, vcc, 0, v7, vcc
	global_load_dwordx4 v[62:65], v[10:11], off offset:2048
	global_load_dwordx4 v[34:37], v[4:5], off offset:-4096
	global_load_dwordx4 v[38:41], v[4:5], off
	global_load_dwordx4 v[42:45], v[4:5], off offset:2048
	v_add_co_u32_e32 v4, vcc, s0, v6
	s_mov_b32 s0, 0xc1000
	s_nop 0
	v_addc_co_u32_e32 v5, vcc, 0, v7, vcc
	v_add_co_u32_e32 v10, vcc, s0, v6
	s_mov_b32 s0, 0xe0000
	s_nop 0
	v_addc_co_u32_e32 v11, vcc, 0, v7, vcc
	v_add_co_u32_e32 v12, vcc, s0, v6
	s_mov_b32 s0, 0xe1000
	s_nop 0
	v_addc_co_u32_e32 v13, vcc, 0, v7, vcc
	v_add_co_u32_e32 v14, vcc, s0, v6
	global_load_dwordx4 v[46:49], v[2:3], off offset:2048
	global_load_dwordx4 v[18:21], v[4:5], off offset:2048
	global_load_dwordx4 v[22:25], v[10:11], off offset:-4096
	global_load_dwordx4 v[26:29], v[10:11], off
	v_addc_co_u32_e32 v15, vcc, 0, v7, vcc
	global_load_dwordx4 v[30:33], v[10:11], off offset:2048
	global_load_dwordx4 v[2:5], v[14:15], off offset:-4096
	global_load_dwordx4 v[126:129], v[8:9], off offset:-4096
	s_nop 0
	global_load_dwordx4 v[6:9], v[12:13], off offset:2048
	s_nop 0
	global_load_dwordx4 v[10:13], v[14:15], off
	s_nop 0
	global_load_dwordx4 v[14:17], v[14:15], off offset:2048
	s_cmp_lg_u64 s[40:41], 0
	s_cselect_b64 s[42:43], -1, 0
	s_lshl_b32 s22, s21, 2
	s_add_u32 s22, s40, s22
	s_addc_u32 s23, s41, 0
	v_ashrrev_i32_e32 v139, 31, v138
	s_cmp_eq_u64 s[40:41], 0
	v_lshl_add_u64 v[136:137], v[138:139], 2, s[22:23]
	s_cbranch_scc1 .LBB0_572
	global_load_dwordx4 v[140:143], v[136:137], off
	global_load_dwordx4 v[212:215], v[136:137], off offset:256
	global_load_dwordx4 v[216:219], v[136:137], off offset:512
	global_load_dwordx4 v[220:223], v[136:137], off offset:768
	global_load_dwordx4 v[224:227], v[136:137], off offset:1024
	global_load_dwordx4 v[228:231], v[136:137], off offset:1280
	global_load_dwordx4 v[232:235], v[136:137], off offset:1536
	global_load_dwordx4 v[236:239], v[136:137], off offset:1792
	s_waitcnt vmcnt(0)
	v_mov_b32_e32 v0, v143
	v_pk_mul_f32 v[110:111], v[110:111], v[140:141] op_sel_hi:[1,0]
	v_pk_mul_f32 v[112:113], v[112:113], v[140:141] op_sel_hi:[1,0]
	v_pk_mul_f32 v[114:115], v[114:115], v[140:141] op_sel:[0,1]
	v_pk_mul_f32 v[116:117], v[116:117], v[140:141] op_sel:[0,1]
	v_pk_mul_f32 v[118:119], v[118:119], v[142:143] op_sel_hi:[1,0]
	v_pk_mul_f32 v[120:121], v[120:121], v[142:143] op_sel_hi:[1,0]
	v_pk_mul_f32 v[122:123], v[122:123], v[0:1] op_sel_hi:[1,0]
	v_pk_mul_f32 v[124:125], v[124:125], v[0:1] op_sel_hi:[1,0]
.LBB0_572:
	s_load_dwordx2 s[22:23], s[12:13], 0x120
	v_mul_u32_u24_e32 v0, 0x240, v133
	v_lshlrev_b32_e32 v133, 1, v138
	s_lshl_b32 s21, s21, 1
	v_add3_u32 v133, 16, v0, v133
	v_lshlrev_b32_e32 v0, 4, v135
	s_waitcnt lgkmcnt(0)
	s_add_u32 s22, s22, s21
	v_ashrrev_i32_e32 v142, 3, v135
	v_and_b32_e32 v0, 0x70, v0
	s_addc_u32 s23, s23, 0
	v_add_u32_e32 v135, 16, v0
	v_lshl_add_u64 v[138:139], s[22:23], 0, v[0:1]
	v_mul_lo_u32 v0, v142, s9
	s_waitcnt vmcnt(28)
	v_cvt_pk_bf16_f32 v141, v118, v122
	v_cvt_pk_bf16_f32 v140, v110, v114
	v_cvt_pk_bf16_f32 v119, v119, v123
	v_cvt_pk_bf16_f32 v118, v111, v115
	v_cvt_pk_bf16_f32 v111, v120, v124
	v_cvt_pk_bf16_f32 v110, v112, v116
	v_cvt_pk_bf16_f32 v115, v121, v125
	v_cvt_pk_bf16_f32 v114, v113, v117
	v_add_u32_e32 v0, v135, v0
	s_barrier
	ds_write2_b64 v133, v[140:141], v[118:119] offset1:18
	ds_write2_b64 v133, v[110:111], v[114:115] offset0:36 offset1:54
	s_waitcnt lgkmcnt(0)
	s_barrier
	ds_read_b128 v[112:115], v0
	ds_read_b128 v[116:119], v0 offset:4608
	v_add_u32_e32 v120, s20, v142
	v_mad_i64_i32 v[110:111], s[20:21], v120, s81, v[138:139]
	s_waitcnt lgkmcnt(1)
	global_store_dwordx4 v[110:111], v[112:115], off
	s_andn2_b64 vcc, exec, s[42:43]
	s_nop 0
	v_add_u32_e32 v112, 32, v120
	v_cndmask_b32_e64 v114, 0, 1, s[42:43]
	v_mad_i64_i32 v[112:113], s[20:21], v112, s81, v[138:139]
	v_cmp_ne_u32_e64 s[40:41], 1, v114
	s_waitcnt lgkmcnt(0)
	global_store_dwordx4 v[112:113], v[116:119], off
	s_cbranch_vccnz .LBB0_574
	v_pk_mul_f32 v[126:127], v[126:127], v[212:213] op_sel_hi:[1,0]
	v_pk_mul_f32 v[128:129], v[128:129], v[212:213] op_sel_hi:[1,0]
	v_pk_mul_f32 v[106:107], v[106:107], v[212:213] op_sel:[0,1]
	v_pk_mul_f32 v[108:109], v[108:109], v[212:213] op_sel:[0,1]
	v_mov_b32_e32 v212, v215
	v_pk_mul_f32 v[98:99], v[98:99], v[214:215] op_sel_hi:[1,0]
	v_pk_mul_f32 v[100:101], v[100:101], v[214:215] op_sel_hi:[1,0]
	v_pk_mul_f32 v[102:103], v[102:103], v[212:213] op_sel_hi:[1,0]
	v_pk_mul_f32 v[104:105], v[104:105], v[212:213] op_sel_hi:[1,0]
.LBB0_574:
	s_waitcnt vmcnt(28)
	v_cvt_pk_bf16_f32 v115, v98, v102
	s_waitcnt vmcnt(5)
	v_cvt_pk_bf16_f32 v114, v126, v106
	v_cvt_pk_bf16_f32 v99, v99, v103
	v_cvt_pk_bf16_f32 v98, v127, v107
	s_barrier
	ds_write2_b64 v133, v[114:115], v[98:99] offset1:18
	v_cvt_pk_bf16_f32 v99, v100, v104
	v_cvt_pk_bf16_f32 v98, v128, v108
	v_cvt_pk_bf16_f32 v101, v101, v105
	v_cvt_pk_bf16_f32 v100, v129, v109
	ds_write2_b64 v133, v[98:99], v[100:101] offset0:36 offset1:54
	s_waitcnt lgkmcnt(0)
	s_barrier
	ds_read_b128 v[98:101], v0
	ds_read_b128 v[102:105], v0 offset:4608
	s_and_b64 vcc, exec, s[40:41]
	s_waitcnt lgkmcnt(1)
	global_store_dwordx4 v[110:111], v[98:101], off offset:128
	s_waitcnt lgkmcnt(0)
	global_store_dwordx4 v[112:113], v[102:105], off offset:128
	s_cbranch_vccnz .LBB0_576
	v_pk_mul_f32 v[86:87], v[86:87], v[216:217] op_sel_hi:[1,0]
	v_pk_mul_f32 v[88:89], v[88:89], v[216:217] op_sel_hi:[1,0]
	v_pk_mul_f32 v[82:83], v[82:83], v[216:217] op_sel:[0,1]
	v_pk_mul_f32 v[84:85], v[84:85], v[216:217] op_sel:[0,1]
	v_mov_b32_e32 v216, v219
	v_pk_mul_f32 v[90:91], v[90:91], v[218:219] op_sel_hi:[1,0]
	v_pk_mul_f32 v[92:93], v[92:93], v[218:219] op_sel_hi:[1,0]
	v_pk_mul_f32 v[94:95], v[94:95], v[216:217] op_sel_hi:[1,0]
	v_pk_mul_f32 v[96:97], v[96:97], v[216:217] op_sel_hi:[1,0]
.LBB0_576:
	v_cvt_pk_bf16_f32 v99, v90, v94
	v_cvt_pk_bf16_f32 v98, v86, v82
	v_cvt_pk_bf16_f32 v91, v91, v95
	v_cvt_pk_bf16_f32 v90, v87, v83
	v_cvt_pk_bf16_f32 v83, v92, v96
	v_cvt_pk_bf16_f32 v82, v88, v84
	v_cvt_pk_bf16_f32 v87, v93, v97
	v_cvt_pk_bf16_f32 v86, v89, v85
	s_barrier
	ds_write2_b64 v133, v[98:99], v[90:91] offset1:18
	ds_write2_b64 v133, v[82:83], v[86:87] offset0:36 offset1:54
	s_waitcnt lgkmcnt(0)
	s_barrier
	ds_read_b128 v[82:85], v0
	ds_read_b128 v[86:89], v0 offset:4608
	s_and_b64 vcc, exec, s[40:41]
	s_waitcnt lgkmcnt(1)
	global_store_dwordx4 v[110:111], v[82:85], off offset:256
	s_waitcnt lgkmcnt(0)
	global_store_dwordx4 v[112:113], v[86:89], off offset:256
	s_cbranch_vccnz .LBB0_578
	v_pk_mul_f32 v[66:67], v[66:67], v[220:221] op_sel_hi:[1,0]
	v_pk_mul_f32 v[68:69], v[68:69], v[220:221] op_sel_hi:[1,0]
	v_pk_mul_f32 v[78:79], v[78:79], v[220:221] op_sel:[0,1]
	v_pk_mul_f32 v[80:81], v[80:81], v[220:221] op_sel:[0,1]
	v_mov_b32_e32 v220, v223
	v_pk_mul_f32 v[70:71], v[70:71], v[222:223] op_sel_hi:[1,0]
	v_pk_mul_f32 v[72:73], v[72:73], v[222:223] op_sel_hi:[1,0]
	v_pk_mul_f32 v[74:75], v[74:75], v[220:221] op_sel_hi:[1,0]
	v_pk_mul_f32 v[76:77], v[76:77], v[220:221] op_sel_hi:[1,0]
.LBB0_578:
	v_cvt_pk_bf16_f32 v83, v70, v74
	v_cvt_pk_bf16_f32 v82, v66, v78
	v_cvt_pk_bf16_f32 v71, v71, v75
	v_cvt_pk_bf16_f32 v70, v67, v79
	s_barrier
	ds_write2_b64 v133, v[82:83], v[70:71] offset1:18
	v_cvt_pk_bf16_f32 v67, v72, v76
	v_cvt_pk_bf16_f32 v66, v68, v80
	v_cvt_pk_bf16_f32 v71, v73, v77
	v_cvt_pk_bf16_f32 v70, v69, v81
	ds_write2_b64 v133, v[66:67], v[70:71] offset0:36 offset1:54
	s_waitcnt lgkmcnt(0)
	s_barrier
	ds_read_b128 v[66:69], v0
	ds_read_b128 v[70:73], v0 offset:4608
	s_and_b64 vcc, exec, s[40:41]
	s_waitcnt lgkmcnt(1)
	global_store_dwordx4 v[110:111], v[66:69], off offset:384
	s_waitcnt lgkmcnt(0)
	global_store_dwordx4 v[112:113], v[70:73], off offset:384
	s_cbranch_vccnz .LBB0_580
	v_pk_mul_f32 v[54:55], v[54:55], v[224:225] op_sel_hi:[1,0]
	v_pk_mul_f32 v[56:57], v[56:57], v[224:225] op_sel_hi:[1,0]
	v_pk_mul_f32 v[50:51], v[50:51], v[224:225] op_sel:[0,1]
	v_pk_mul_f32 v[52:53], v[52:53], v[224:225] op_sel:[0,1]
	v_mov_b32_e32 v224, v227
	v_pk_mul_f32 v[58:59], v[58:59], v[226:227] op_sel_hi:[1,0]
	v_pk_mul_f32 v[60:61], v[60:61], v[226:227] op_sel_hi:[1,0]
	v_pk_mul_f32 v[62:63], v[62:63], v[224:225] op_sel_hi:[1,0]
	v_pk_mul_f32 v[64:65], v[64:65], v[224:225] op_sel_hi:[1,0]
.LBB0_580:
	v_cvt_pk_bf16_f32 v67, v58, v62
	v_cvt_pk_bf16_f32 v66, v54, v50
	v_cvt_pk_bf16_f32 v59, v59, v63
	v_cvt_pk_bf16_f32 v58, v55, v51
	v_cvt_pk_bf16_f32 v51, v60, v64
	v_cvt_pk_bf16_f32 v50, v56, v52
	v_cvt_pk_bf16_f32 v55, v61, v65
	v_cvt_pk_bf16_f32 v54, v57, v53
	s_barrier
	ds_write2_b64 v133, v[66:67], v[58:59] offset1:18
	ds_write2_b64 v133, v[50:51], v[54:55] offset0:36 offset1:54
	s_waitcnt lgkmcnt(0)
	s_barrier
	ds_read_b128 v[50:53], v0
	ds_read_b128 v[54:57], v0 offset:4608
	s_and_b64 vcc, exec, s[40:41]
	s_waitcnt lgkmcnt(1)
	global_store_dwordx4 v[110:111], v[50:53], off offset:512
	s_waitcnt lgkmcnt(0)
	global_store_dwordx4 v[112:113], v[54:57], off offset:512
	s_cbranch_vccnz .LBB0_582
	v_pk_mul_f32 v[34:35], v[34:35], v[228:229] op_sel_hi:[1,0]
	v_pk_mul_f32 v[36:37], v[36:37], v[228:229] op_sel_hi:[1,0]
	v_pk_mul_f32 v[46:47], v[46:47], v[228:229] op_sel:[0,1]
	v_pk_mul_f32 v[48:49], v[48:49], v[228:229] op_sel:[0,1]
	v_mov_b32_e32 v228, v231
	v_pk_mul_f32 v[38:39], v[38:39], v[230:231] op_sel_hi:[1,0]
	v_pk_mul_f32 v[40:41], v[40:41], v[230:231] op_sel_hi:[1,0]
	v_pk_mul_f32 v[42:43], v[42:43], v[228:229] op_sel_hi:[1,0]
	v_pk_mul_f32 v[44:45], v[44:45], v[228:229] op_sel_hi:[1,0]
.LBB0_582:
	v_cvt_pk_bf16_f32 v51, v38, v42
	v_cvt_pk_bf16_f32 v50, v34, v46
	v_cvt_pk_bf16_f32 v39, v39, v43
	v_cvt_pk_bf16_f32 v38, v35, v47
	s_barrier
	ds_write2_b64 v133, v[50:51], v[38:39] offset1:18
	v_cvt_pk_bf16_f32 v35, v40, v44
	v_cvt_pk_bf16_f32 v34, v36, v48
	v_cvt_pk_bf16_f32 v39, v41, v45
	v_cvt_pk_bf16_f32 v38, v37, v49
	ds_write2_b64 v133, v[34:35], v[38:39] offset0:36 offset1:54
	s_waitcnt lgkmcnt(0)
	s_barrier
	ds_read_b128 v[34:37], v0
	ds_read_b128 v[38:41], v0 offset:4608
	s_and_b64 vcc, exec, s[40:41]
	s_waitcnt lgkmcnt(1)
	global_store_dwordx4 v[110:111], v[34:37], off offset:640
	s_waitcnt lgkmcnt(0)
	global_store_dwordx4 v[112:113], v[38:41], off offset:640
	s_cbranch_vccnz .LBB0_584
	v_pk_mul_f32 v[22:23], v[22:23], v[232:233] op_sel_hi:[1,0]
	v_pk_mul_f32 v[24:25], v[24:25], v[232:233] op_sel_hi:[1,0]
	v_pk_mul_f32 v[18:19], v[18:19], v[232:233] op_sel:[0,1]
	v_pk_mul_f32 v[20:21], v[20:21], v[232:233] op_sel:[0,1]
	v_mov_b32_e32 v232, v235
	v_pk_mul_f32 v[26:27], v[26:27], v[234:235] op_sel_hi:[1,0]
	v_pk_mul_f32 v[28:29], v[28:29], v[234:235] op_sel_hi:[1,0]
	v_pk_mul_f32 v[30:31], v[30:31], v[232:233] op_sel_hi:[1,0]
	v_pk_mul_f32 v[32:33], v[32:33], v[232:233] op_sel_hi:[1,0]
.LBB0_584:
	v_cvt_pk_bf16_f32 v35, v26, v30
	v_cvt_pk_bf16_f32 v34, v22, v18
	v_cvt_pk_bf16_f32 v27, v27, v31
	v_cvt_pk_bf16_f32 v26, v23, v19
	v_cvt_pk_bf16_f32 v19, v28, v32
	v_cvt_pk_bf16_f32 v18, v24, v20
	v_cvt_pk_bf16_f32 v23, v29, v33
	v_cvt_pk_bf16_f32 v22, v25, v21
	s_barrier
	ds_write2_b64 v133, v[34:35], v[26:27] offset1:18
	ds_write2_b64 v133, v[18:19], v[22:23] offset0:36 offset1:54
	s_waitcnt lgkmcnt(0)
	s_barrier
	ds_read_b128 v[18:21], v0
	ds_read_b128 v[22:25], v0 offset:4608
	s_and_b64 vcc, exec, s[40:41]
	s_waitcnt lgkmcnt(1)
	global_store_dwordx4 v[110:111], v[18:21], off offset:768
	s_waitcnt lgkmcnt(0)
	global_store_dwordx4 v[112:113], v[22:25], off offset:768
	s_cbranch_vccnz .LBB0_586
	v_pk_mul_f32 v[2:3], v[2:3], v[236:237] op_sel_hi:[1,0]
	v_pk_mul_f32 v[4:5], v[4:5], v[236:237] op_sel_hi:[1,0]
	v_pk_mul_f32 v[6:7], v[6:7], v[236:237] op_sel:[0,1]
	v_pk_mul_f32 v[8:9], v[8:9], v[236:237] op_sel:[0,1]
	v_mov_b32_e32 v236, v239
	v_pk_mul_f32 v[10:11], v[10:11], v[238:239] op_sel_hi:[1,0]
	v_pk_mul_f32 v[12:13], v[12:13], v[238:239] op_sel_hi:[1,0]
	v_pk_mul_f32 v[14:15], v[14:15], v[236:237] op_sel_hi:[1,0]
	v_pk_mul_f32 v[16:17], v[16:17], v[236:237] op_sel_hi:[1,0]
